# hand-written sliding-window attention phase (K/V staged in LDS, S^T=K.Q^T MFMA, softmax in registers, V^T via tr-reads)
# speedup vs baseline: 1.0635x; 1.0068x over previous
; #define LAS __attribute__((address_space(3)))
; __device__ __forceinline__ int otid() { int t = threadIdx.x; asm volatile("" : "+v"(t)); return t; }
; __device__ __forceinline__ int obid() { int b = blockIdx.x; asm volatile("" : "+s"(b)); return b; }
; __device__ __forceinline__ void phase_attn(const Params& p, int l, LAS unsigned char* ldsb) {
;     unsigned char* R = p.ws + WS_R;
;     const bf16_t* QKV = (const bf16_t*)(R + R_QKV); bf16_t* ATT = (bf16_t*)(R + R_ATT);
;     const float* relb = p.in[7]; const float* sinks = p.in[8] + l * 8;
;     const int tid = otid(), wid = tid >> 6, lane = tid & 63, fr = lane & 15, fq = lane >> 4;
;     LAS bf16_t* Ks = (LAS bf16_t*)ldsb;
;     LAS bf16_t* Vt = (LAS bf16_t*)(ldsb + 36864);
;     LAS float* biasL = (LAS float*)(ldsb + 70656);
;     LAS bf16_t* Pw = (LAS bf16_t*)(ldsb + 72704) + wid * (16 * 168);
;     for (int item = obid(); item < 512; item += gridDim.x) {
;         const int g = item & 1, n = (item >> 1) & 31, b = item >> 6;
;         const long tokc = (long)b * SEQ + n * 128, tokp = tokc - 128;
;         for (int idx = tid; idx < 2048; idx += 512) {
;             const int key = idx >> 3, d8 = idx & 7; u32x4 v = (u32x4){0u, 0u, 0u, 0u}, kv = (u32x4){0u, 0u, 0u, 0u};
;             if (n > 0 || key >= 128) { const bf16_t* src = QKV + (size_t)(tokp + key) * 768 + 512 + g * 64 + d8 * 8; kv = *(const u32x4*)src; v = *(const u32x4*)(src + 128); }
;             *(LAS u32x4*)(Ks + key * 72 + d8 * 8) = kv;
; #pragma unroll
;             for (int e = 0; e < 8; ++e) Vt[(d8 * 8 + e) * 264 + key] = (bf16_t)((e & 1) ? (v[e >> 1] >> 16) : (v[e >> 1] & 0xffffu));
;         }
;         { const int hl = tid >> 7, d = tid & 127; int bk = d;
;           if (d >= 16) { bk = 16 + (int)(__logf((float)d * 0.0625f) * (16.f / 2.07944154168f)); bk = bk > 31 ? 31 : bk; }
;           biasL[tid] = relb[bk * 8 + g * 4 + hl]; }
.Lat_entry:
	v_and_b32_e32 v0, 63, v183
	v_and_b32_e32 v1, 15, v183
	v_bfe_u32 v2, v183, 4, 2
	v_lshrrev_b32_e32 v4, 6, v183
	s_nop 0
	v_readfirstlane_b32 s45, v4
	s_nop 0
	s_lshr_b32 s46, s45, 1
	s_and_b32 s47, s45, 1
	v_readlane_b32 s0, v252, 0
	v_readlane_b32 s1, v252, 1
	s_sub_u32 s0, s0, 0xe0
	s_subb_u32 s1, s1, 0
	s_load_dwordx2 s[14:15], s[0:1], 0x38
	s_load_dwordx2 s[26:27], s[0:1], 0x40
	v_readlane_b32 s86, v243, 45
	s_nop 0
	s_lshr_b32 s86, s86, 1
	s_mov_b32 s83, 0x3e38aa3b
	v_lshrrev_b32_e32 v4, 3, v183
	v_and_b32_e32 v5, 7, v183
	v_mul_u32_u24_e32 v6, 1536, v4
	v_lshl_add_u32 v6, v5, 4, v6
	v_and_b32_e32 v3, 7, v4
	v_xor_b32_e32 v3, v3, v5
	v_lshlrev_b32_e32 v3, 4, v3
	v_lshl_add_u32 v3, v4, 7, v3
	v_and_b32_e32 v7, 127, v183
	v_lshrrev_b32_e32 v4, 7, v183
	v_cvt_f32_u32_e32 v5, v7
	v_mul_f32_e32 v5, 0x3d800000, v5
	v_max_f32_e32 v5, 1.0, v5
	v_log_f32_e32 v5, v5
	s_nop 0
	v_mul_f32_e32 v5, 0x40aaaaab, v5
	v_cvt_i32_f32_e32 v5, v5
	v_add_u32_e32 v5, 16, v5
	v_min_u32_e32 v5, 31, v5
	v_cmp_gt_u32_e32 vcc, 16, v7
	s_nop 1
	v_cndmask_b32_e32 v9, v5, v7, vcc
	v_lshlrev_b32_e32 v9, 5, v9
	v_lshl_add_u32 v9, v4, 2, v9
	v_mul_u32_u24_e32 v8, 3136, v4
	v_sub_u32_e32 v5, 160, v7
	v_lshl_add_u32 v8, v5, 2, v8
	v_add_u32_e32 v8, 65536, v8
	v_add_u32_e32 v5, 96, v7
	v_subrev_u32_e32 v28, 32, v7
	v_cmp_gt_u32_e32 vcc, 32, v7
	s_nop 1
	v_cndmask_b32_e32 v5, v5, v28, vcc
	v_sub_u32_e32 v5, 160, v5
	v_mul_u32_u24_e32 v10, 3136, v4
	v_lshl_add_u32 v10, v5, 2, v10
	v_add_u32_e32 v10, 65536, v10
	v_lshlrev_b32_e32 v5, 4, v183
	v_add_u32_e32 v5, 75716, v5
	v_cmp_gt_u32_e32 vcc, 65, v7
	s_nop 1
	v_cndmask_b32_e32 v10, v5, v10, vcc
	v_and_b32_e32 v4, 7, v1
	v_xor_b32_e32 v4, v4, v2
	v_lshlrev_b32_e32 v4, 4, v4
	v_lshl_add_u32 v11, v1, 7, v4
	v_xor_b32_e32 v13, 64, v11
	v_and_b32_e32 v4, 3, v1
	v_mul_u32_u24_e32 v16, 784, v4
	v_and_b32_e32 v4, 12, v1
	v_lshlrev_b32_e32 v4, 2, v4
	v_sub_u32_e32 v16, v16, v4
	v_lshl_add_u32 v16, v2, 4, v16
	s_mul_i32 s81, s46, 3136
	s_add_u32 s81, s81, 65536
	v_add_u32_e32 v16, s81, v16
	v_lshrrev_b32_e32 v4, 2, v1
	v_lshl_add_u32 v4, v2, 2, v4
	v_and_b32_e32 v5, 7, v4
	v_bfe_u32 v28, v1, 1, 1
	v_and_b32_e32 v29, 1, v1
	v_lshlrev_b32_e32 v29, 3, v29
	v_lshl_add_u32 v29, v4, 7, v29
	v_add_u32_e32 v29, 32768, v29
	v_or_b32_e32 v4, 0, v28
	v_xor_b32_e32 v4, v4, v5
	v_lshl_add_u32 v18, v4, 4, v29
	v_or_b32_e32 v4, 2, v28
	v_xor_b32_e32 v4, v4, v5
	v_lshl_add_u32 v19, v4, 4, v29
	v_or_b32_e32 v4, 4, v28
	v_xor_b32_e32 v4, v4, v5
	v_lshl_add_u32 v20, v4, 4, v29
	v_or_b32_e32 v4, 6, v28
	v_xor_b32_e32 v4, v4, v5
	v_lshl_add_u32 v21, v4, 4, v29
	v_mul_u32_u24_e32 v26, 1536, v1
	v_lshl_add_u32 v26, v2, 4, v26
	v_lshlrev_b32_e32 v27, 10, v1
	v_lshl_add_u32 v27, v2, 3, v27
	v_xor_b32_e32 v28, 16, v0
	v_lshlrev_b32_e32 v28, 2, v28
	v_xor_b32_e32 v29, 32, v0
	v_lshlrev_b32_e32 v29, 2, v29
	s_mov_b32 s2, s5
	s_waitcnt lgkmcnt(0)
	s_lshl_b32 s81, s86, 5
	s_add_u32 s26, s26, s81
	s_addc_u32 s27, s27, 0
.Lat_item:
	s_and_b32 s13, s2, 1
	s_lshr_b32 s25, s2, 1
	s_and_b32 s25, s25, 31
	s_lshr_b32 s32, s2, 6
	s_lshl_b32 s44, s32, 12
	s_lshl_b32 s81, s25, 7
	s_add_u32 s44, s44, s81
	s_lshl_b32 s48, s13, 2
	s_add_u32 s48, s48, s46
	s_lshl_b32 s81, s13, 4
	v_add_u32_e32 v4, s81, v9
	global_load_dword v33, v4, s[14:15]
	s_lshl_b32 s81, s48, 2
	s_add_u32 s36, s26, s81
	s_addc_u32 s37, s27, 0
	s_load_dword s84, s[36:37], 0x0
	s_sub_u32 s81, s44, 128
	s_mul_i32 s81, s81, 1536
	s_lshl_b32 s82, s13, 7
	s_add_u32 s81, s81, s82
	s_add_u32 s81, s81, 1024
	s_add_u32 s36, s74, s81
	s_addc_u32 s37, s75, 0
	s_cmp_eq_u32 s25, 0
	s_cbranch_scc1 .Lat_stage_n0
	global_load_dwordx4 v[60:63], v6, s[36:37]
	global_load_dwordx4 v[64:67], v6, s[36:37] offset:256
	s_add_u32 s36, s36, 98304
	s_addc_u32 s37, s37, 0
	global_load_dwordx4 v[68:71], v6, s[36:37]
	global_load_dwordx4 v[72:75], v6, s[36:37] offset:256
	s_add_u32 s36, s36, 98304
	s_addc_u32 s37, s37, 0
	global_load_dwordx4 v[76:79], v6, s[36:37]
	global_load_dwordx4 v[80:83], v6, s[36:37] offset:256
	s_add_u32 s36, s36, 98304
	s_addc_u32 s37, s37, 0
	global_load_dwordx4 v[84:87], v6, s[36:37]
	global_load_dwordx4 v[88:91], v6, s[36:37] offset:256
	s_waitcnt vmcnt(6)
	ds_write_b128 v3, v[60:63] offset:0
	ds_write_b128 v3, v[64:67] offset:32768
	s_waitcnt vmcnt(4)
	ds_write_b128 v3, v[68:71] offset:8192
	ds_write_b128 v3, v[72:75] offset:40960
	s_waitcnt vmcnt(2)
	ds_write_b128 v3, v[76:79] offset:16384
	ds_write_b128 v3, v[80:83] offset:49152
	s_waitcnt vmcnt(0)
	ds_write_b128 v3, v[84:87] offset:24576
	ds_write_b128 v3, v[88:91] offset:57344
	s_branch .Lat_staged
.Lat_stage_n0:
	s_mul_i32 s81, s44, 1536
	s_add_u32 s81, s81, s82
	s_add_u32 s81, s81, 1024
	s_add_u32 s36, s74, s81
	s_addc_u32 s37, s75, 0
	global_load_dwordx4 v[76:79], v6, s[36:37]
	global_load_dwordx4 v[80:83], v6, s[36:37] offset:256
	s_add_u32 s36, s36, 98304
	s_addc_u32 s37, s37, 0
	global_load_dwordx4 v[84:87], v6, s[36:37]
	global_load_dwordx4 v[88:91], v6, s[36:37] offset:256
	v_mov_b32_e32 v60, 0
	v_mov_b32_e32 v61, 0
	v_mov_b32_e32 v62, 0
	v_mov_b32_e32 v63, 0
	ds_write_b128 v3, v[60:63] offset:0
	ds_write_b128 v3, v[60:63] offset:32768
	ds_write_b128 v3, v[60:63] offset:8192
	ds_write_b128 v3, v[60:63] offset:40960
	s_waitcnt vmcnt(2)
	ds_write_b128 v3, v[76:79] offset:16384
	ds_write_b128 v3, v[80:83] offset:49152
	s_waitcnt vmcnt(0)
	ds_write_b128 v3, v[84:87] offset:24576
	ds_write_b128 v3, v[88:91] offset:57344
; #define LAS __attribute__((address_space(3)))
; __device__ __forceinline__ void phase_attn(const Params& p, int l, LAS unsigned char* ldsb) {
;     ...
;         __syncthreads();
;         const int hl = wid >> 1, hq = g * 4 + hl; const float sink = sinks[hq];
;         for (int rt = 0; rt < 4; ++rt) {
;             const int q0 = (wid & 1) * 64 + rt * 16, kstart = q0 < 96 ? q0 : 96;
;             bf16x8 qa0, qa1; { const bf16_t* qp = QKV + (size_t)(tokc + q0 + fr) * 768 + hq * 64 + fq * 8; qa0 = *(const bf16x8*)qp; qa1 = *(const bf16x8*)(qp + 32); }
;             f32x4 S[10];
; #pragma unroll
;             for (int kt = 0; kt < 10; ++kt) {
;                 LAS const bf16_t* kp = Ks + (kstart + kt * 16 + fr) * 72 + fq * 8;
;                 const bf16x8 k0 = *(LAS const bf16x8*)kp, k1 = *(LAS const bf16x8*)(kp + 32);
;                 f32x4 z = (f32x4){0.f, 0.f, 0.f, 0.f};
;                 z = __builtin_amdgcn_mfma_f32_16x16x32_bf16(qa0, k0, z, 0, 0, 0);
;                 z = __builtin_amdgcn_mfma_f32_16x16x32_bf16(qa1, k1, z, 0, 0, 0);
;                 S[kt] = z;
;             }
;             float mx[4] = {-INFINITY, -INFINITY, -INFINITY, -INFINITY};
; #pragma unroll
;             for (int kt = 0; kt < 10; ++kt)
; #pragma unroll
;                 for (int j = 0; j < 4; ++j) {
;                     const int key = kstart + kt * 16 + fr, dist = q0 + 4 * fq + j + 128 - key;
;                     const bool ok = (dist >= 0) && (dist < 128) && (n > 0 || key >= 128);
;                     const float s = ok ? (S[kt][j] * 0.125f + biasL[hl * 128 + (dist & 127)]) : -INFINITY;
;                     S[kt][j] = s; mx[j] = fmaxf(mx[j], s);
;                 }
.Lat_staged:
	s_waitcnt vmcnt(0)
	v_mul_f32_e32 v33, 0x3fb8aa3b, v33
	v_mov_b32_e32 v34, 0xff800000
	ds_write_b32 v8, v33 offset:0
	ds_write_b32 v10, v34 offset:0
	ds_write_b32 v8, v33 offset:788
	ds_write_b32 v10, v34 offset:788
	ds_write_b32 v8, v33 offset:1576
	ds_write_b32 v10, v34 offset:1576
	ds_write_b32 v8, v33 offset:2364
	ds_write_b32 v10, v34 offset:2364
	s_waitcnt lgkmcnt(0)
	s_barrier
	v_mov_b32_e32 v4, s84
	v_mul_f32_e32 v4, 0x3fb8aa3b, v4
	s_nop 0
	v_readfirstlane_b32 s84, v4
	s_mov_b32 s49, 0
	s_nop 3
.Lat_rt:
	s_lshl_b32 s50, s47, 6
	s_lshl_b32 s81, s49, 4
	s_add_u32 s50, s50, s81
	s_min_u32 s51, s50, 96
	s_add_u32 s81, s44, s50
	s_mul_i32 s82, s81, 1536
	s_lshl_b32 s85, s48, 7
	s_add_u32 s82, s82, s85
	s_add_u32 s40, s74, s82
	s_addc_u32 s41, s75, 0
	global_load_dwordx4 v[36:39], v26, s[40:41]
	global_load_dwordx4 v[40:43], v26, s[40:41] offset:64
	s_lshl_b32 s82, s81, 10
	s_add_u32 s82, s82, s85
	s_add_u32 s82, s82, 0x7000000
	s_add_u32 s42, s74, s82
	s_addc_u32 s43, s75, 0
	s_lshl_b32 s81, s51, 7
	v_add_u32_e32 v14, s81, v11
	v_add_u32_e32 v15, s81, v13
	v_add_u32_e32 v22, s81, v18
	v_add_u32_e32 v23, s81, v19
	v_add_u32_e32 v24, s81, v20
	v_add_u32_e32 v25, s81, v21
	s_sub_u32 s82, s50, s51
	s_sub_u32 s82, 32, s82
	s_lshl_b32 s82, s82, 2
	v_add_u32_e32 v17, s82, v16
	s_sub_u32 s85, 128, s51
	s_lshr_b32 s85, s85, 4
	s_cmp_eq_u32 s25, 0
	s_cselect_b32 s85, s85, 0
	ds_read_b128 v[100:103], v17 offset:0
	ds_read_b128 v[104:107], v17 offset:64
	ds_read_b128 v[108:111], v17 offset:128
	ds_read_b128 v[112:115], v17 offset:192
	ds_read_b128 v[116:119], v17 offset:256
	ds_read_b128 v[120:123], v17 offset:320
	ds_read_b128 v[124:127], v17 offset:384
	ds_read_b128 v[128:131], v17 offset:448
	ds_read_b128 v[132:135], v17 offset:512
	ds_read_b128 v[136:139], v17 offset:576
	ds_read_b128 v[44:47], v14 offset:0
	ds_read_b128 v[48:51], v15 offset:0
	ds_read_b128 v[52:55], v14 offset:2048
	ds_read_b128 v[56:59], v15 offset:2048
	s_waitcnt vmcnt(0)
	s_waitcnt lgkmcnt(2)
	v_mfma_f32_16x16x32_bf16 v[60:63], v[44:47], v[36:39], 0
	v_mfma_f32_16x16x32_bf16 v[60:63], v[48:51], v[40:43], v[60:63]
	ds_read_b128 v[44:47], v14 offset:4096
	ds_read_b128 v[48:51], v15 offset:4096
	s_waitcnt lgkmcnt(2)
	v_mfma_f32_16x16x32_bf16 v[64:67], v[52:55], v[36:39], 0
	v_mfma_f32_16x16x32_bf16 v[64:67], v[56:59], v[40:43], v[64:67]
	ds_read_b128 v[52:55], v14 offset:6144
	ds_read_b128 v[56:59], v15 offset:6144
	s_waitcnt lgkmcnt(2)
	v_mfma_f32_16x16x32_bf16 v[68:71], v[44:47], v[36:39], 0
	v_mfma_f32_16x16x32_bf16 v[68:71], v[48:51], v[40:43], v[68:71]
	ds_read_b128 v[44:47], v14 offset:8192
	ds_read_b128 v[48:51], v15 offset:8192
	s_waitcnt lgkmcnt(2)
	v_mfma_f32_16x16x32_bf16 v[72:75], v[52:55], v[36:39], 0
	v_mfma_f32_16x16x32_bf16 v[72:75], v[56:59], v[40:43], v[72:75]
	ds_read_b128 v[52:55], v14 offset:10240
	ds_read_b128 v[56:59], v15 offset:10240
	s_waitcnt lgkmcnt(2)
	v_mfma_f32_16x16x32_bf16 v[76:79], v[44:47], v[36:39], 0
	v_mfma_f32_16x16x32_bf16 v[76:79], v[48:51], v[40:43], v[76:79]
	ds_read_b128 v[44:47], v14 offset:12288
	ds_read_b128 v[48:51], v15 offset:12288
	s_waitcnt lgkmcnt(2)
	v_mfma_f32_16x16x32_bf16 v[80:83], v[52:55], v[36:39], 0
	v_mfma_f32_16x16x32_bf16 v[80:83], v[56:59], v[40:43], v[80:83]
	ds_read_b128 v[52:55], v14 offset:14336
	ds_read_b128 v[56:59], v15 offset:14336
	s_waitcnt lgkmcnt(2)
	v_mfma_f32_16x16x32_bf16 v[84:87], v[44:47], v[36:39], 0
	v_mfma_f32_16x16x32_bf16 v[84:87], v[48:51], v[40:43], v[84:87]
	ds_read_b128 v[44:47], v14 offset:16384
	ds_read_b128 v[48:51], v15 offset:16384
	s_waitcnt lgkmcnt(2)
	v_mfma_f32_16x16x32_bf16 v[88:91], v[52:55], v[36:39], 0
	v_mfma_f32_16x16x32_bf16 v[88:91], v[56:59], v[40:43], v[88:91]
	ds_read_b128 v[52:55], v14 offset:18432
	ds_read_b128 v[56:59], v15 offset:18432
	s_waitcnt lgkmcnt(2)
	v_mfma_f32_16x16x32_bf16 v[92:95], v[44:47], v[36:39], 0
	v_mfma_f32_16x16x32_bf16 v[92:95], v[48:51], v[40:43], v[92:95]
	s_waitcnt lgkmcnt(0)
	v_mfma_f32_16x16x32_bf16 v[96:99], v[52:55], v[36:39], 0
	v_mfma_f32_16x16x32_bf16 v[96:99], v[56:59], v[40:43], v[96:99]
	v_fma_f32 v60, v60, s83, v100
	v_fma_f32 v61, v61, s83, v101
	v_fma_f32 v62, v62, s83, v102
	v_fma_f32 v63, v63, s83, v103
	v_fma_f32 v64, v64, s83, v104
	v_fma_f32 v65, v65, s83, v105
	v_fma_f32 v66, v66, s83, v106
	v_fma_f32 v67, v67, s83, v107
	v_fma_f32 v68, v68, s83, v108
	v_fma_f32 v69, v69, s83, v109
	v_fma_f32 v70, v70, s83, v110
	v_fma_f32 v71, v71, s83, v111
	v_fma_f32 v72, v72, s83, v112
	v_fma_f32 v73, v73, s83, v113
	v_fma_f32 v74, v74, s83, v114
	v_fma_f32 v75, v75, s83, v115
	v_fma_f32 v76, v76, s83, v116
	v_fma_f32 v77, v77, s83, v117
	v_fma_f32 v78, v78, s83, v118
	v_fma_f32 v79, v79, s83, v119
	v_fma_f32 v80, v80, s83, v120
	v_fma_f32 v81, v81, s83, v121
	v_fma_f32 v82, v82, s83, v122
	v_fma_f32 v83, v83, s83, v123
	v_fma_f32 v84, v84, s83, v124
	v_fma_f32 v85, v85, s83, v125
	v_fma_f32 v86, v86, s83, v126
	v_fma_f32 v87, v87, s83, v127
	v_fma_f32 v88, v88, s83, v128
	v_fma_f32 v89, v89, s83, v129
	v_fma_f32 v90, v90, s83, v130
	v_fma_f32 v91, v91, s83, v131
	v_fma_f32 v92, v92, s83, v132
	v_fma_f32 v93, v93, s83, v133
	v_fma_f32 v94, v94, s83, v134
	v_fma_f32 v95, v95, s83, v135
	v_fma_f32 v96, v96, s83, v136
	v_fma_f32 v97, v97, s83, v137
	v_fma_f32 v98, v98, s83, v138
	v_fma_f32 v99, v99, s83, v139
	s_cmp_eq_u32 s85, 0
	s_nop 0
	s_cbranch_scc1 .Lat_nomask
	s_cmp_gt_u32 s85, 0
	s_cselect_b32 s87, 0xff800000, 0
	v_add_f32_e32 v60, s87, v60
	v_add_f32_e32 v61, s87, v61
	v_add_f32_e32 v62, s87, v62
	v_add_f32_e32 v63, s87, v63
	s_cmp_gt_u32 s85, 1
	s_cselect_b32 s87, 0xff800000, 0
	v_add_f32_e32 v64, s87, v64
	v_add_f32_e32 v65, s87, v65
	v_add_f32_e32 v66, s87, v66
	v_add_f32_e32 v67, s87, v67
	s_cmp_gt_u32 s85, 2
	s_cselect_b32 s87, 0xff800000, 0
	v_add_f32_e32 v68, s87, v68
	v_add_f32_e32 v69, s87, v69
	v_add_f32_e32 v70, s87, v70
	v_add_f32_e32 v71, s87, v71
	s_cmp_gt_u32 s85, 3
	s_cselect_b32 s87, 0xff800000, 0
	v_add_f32_e32 v72, s87, v72
	v_add_f32_e32 v73, s87, v73
	v_add_f32_e32 v74, s87, v74
	v_add_f32_e32 v75, s87, v75
	s_cmp_gt_u32 s85, 4
	s_cselect_b32 s87, 0xff800000, 0
	v_add_f32_e32 v76, s87, v76
	v_add_f32_e32 v77, s87, v77
	v_add_f32_e32 v78, s87, v78
	v_add_f32_e32 v79, s87, v79
	s_cmp_gt_u32 s85, 5
	s_cselect_b32 s87, 0xff800000, 0
	v_add_f32_e32 v80, s87, v80
	v_add_f32_e32 v81, s87, v81
	v_add_f32_e32 v82, s87, v82
	v_add_f32_e32 v83, s87, v83
	s_cmp_gt_u32 s85, 6
	s_cselect_b32 s87, 0xff800000, 0
	v_add_f32_e32 v84, s87, v84
	v_add_f32_e32 v85, s87, v85
	v_add_f32_e32 v86, s87, v86
	v_add_f32_e32 v87, s87, v87
	s_cmp_gt_u32 s85, 7
	s_cselect_b32 s87, 0xff800000, 0
	v_add_f32_e32 v88, s87, v88
	v_add_f32_e32 v89, s87, v89
	v_add_f32_e32 v90, s87, v90
	v_add_f32_e32 v91, s87, v91
	s_nop 1
; #define LAS __attribute__((address_space(3)))
; __device__ __forceinline__ unsigned pk_bf16(float lo, float hi) { const f32x2_t f = {lo, hi}; return __builtin_bit_cast(unsigned, __builtin_convertvector(f, bf16x2_t)); }
; __device__ __forceinline__ void phase_attn(const Params& p, int l, LAS unsigned char* ldsb) {
;     ...
;             float inv[4];
; #pragma unroll
;             for (int j = 0; j < 4; ++j) mx[j] = fmaxf(row16_max(mx[j]), sink);
;             float sm[4] = {0.f, 0.f, 0.f, 0.f};
; #pragma unroll
;             for (int kt = 0; kt < 10; ++kt)
; #pragma unroll
;                 for (int j = 0; j < 4; ++j) { const float e = __expf(S[kt][j] - mx[j]); S[kt][j] = e; sm[j] += e; }
; #pragma unroll
;             for (int j = 0; j < 4; ++j) inv[j] = 1.f / (row16_sum(sm[j]) + __expf(sink - mx[j]));
; #pragma unroll
;             for (int kt = 0; kt < 10; ++kt)
; #pragma unroll
;                 for (int j = 0; j < 4; ++j) Pw[(4 * fq + j) * 168 + kt * 16 + fr] = (bf16_t)(pk_bf16(S[kt][j] * inv[j], 0.f) & 0xffffu);
;             asm volatile("s_waitcnt lgkmcnt(0)" ::: "memory");
;             __builtin_amdgcn_wave_barrier();
;             f32x4 O[4];
; #pragma unroll
;             for (int dt = 0; dt < 4; ++dt) O[dt] = (f32x4){0.f, 0.f, 0.f, 0.f};
; #pragma unroll
;             for (int kk = 0; kk < 5; ++kk) {
;                 const bf16x8 pa = *(LAS const bf16x8*)(Pw + fr * 168 + kk * 32 + fq * 8);
; #pragma unroll
;                 for (int dt = 0; dt < 4; ++dt) {
;                     const bf16x8 vb = *(LAS const bf16x8*)(Vt + (dt * 16 + fr) * 264 + kstart + kk * 32 + fq * 8);
.Lat_nomask:
	v_max3_f32 v30, v60, v61, v62
	v_max3_f32 v30, v30, v63, v64
	v_max3_f32 v30, v30, v65, v66
	v_max3_f32 v30, v30, v67, v68
	v_max3_f32 v30, v30, v69, v70
	v_max3_f32 v30, v30, v71, v72
	v_max3_f32 v30, v30, v73, v74
	v_max3_f32 v30, v30, v75, v76
	v_max3_f32 v30, v30, v77, v78
	v_max3_f32 v30, v30, v79, v80
	v_max3_f32 v30, v30, v81, v82
	v_max3_f32 v30, v30, v83, v84
	v_max3_f32 v30, v30, v85, v86
	v_max3_f32 v30, v30, v87, v88
	v_max3_f32 v30, v30, v89, v90
	v_max3_f32 v30, v30, v91, v92
	v_max3_f32 v30, v30, v93, v94
	v_max3_f32 v30, v30, v95, v96
	v_max3_f32 v30, v30, v97, v98
	v_max_f32_e32 v30, v30, v99
	ds_bpermute_b32 v33, v28, v30
	s_waitcnt lgkmcnt(0)
	v_max_f32_e32 v30, v30, v33
	ds_bpermute_b32 v33, v29, v30
	s_waitcnt lgkmcnt(0)
	v_max_f32_e32 v30, v30, v33
	v_max_f32_e32 v30, s84, v30
	v_sub_f32_e32 v60, v60, v30
	v_sub_f32_e32 v61, v61, v30
	v_sub_f32_e32 v62, v62, v30
	v_sub_f32_e32 v63, v63, v30
	v_sub_f32_e32 v64, v64, v30
	v_sub_f32_e32 v65, v65, v30
	v_sub_f32_e32 v66, v66, v30
	v_sub_f32_e32 v67, v67, v30
	v_sub_f32_e32 v68, v68, v30
	v_sub_f32_e32 v69, v69, v30
	v_sub_f32_e32 v70, v70, v30
	v_sub_f32_e32 v71, v71, v30
	v_sub_f32_e32 v72, v72, v30
	v_sub_f32_e32 v73, v73, v30
	v_sub_f32_e32 v74, v74, v30
	v_sub_f32_e32 v75, v75, v30
	v_sub_f32_e32 v76, v76, v30
	v_sub_f32_e32 v77, v77, v30
	v_sub_f32_e32 v78, v78, v30
	v_sub_f32_e32 v79, v79, v30
	v_sub_f32_e32 v80, v80, v30
	v_sub_f32_e32 v81, v81, v30
	v_sub_f32_e32 v82, v82, v30
	v_sub_f32_e32 v83, v83, v30
	v_sub_f32_e32 v84, v84, v30
	v_sub_f32_e32 v85, v85, v30
	v_sub_f32_e32 v86, v86, v30
	v_sub_f32_e32 v87, v87, v30
	v_sub_f32_e32 v88, v88, v30
	v_sub_f32_e32 v89, v89, v30
	v_sub_f32_e32 v90, v90, v30
	v_sub_f32_e32 v91, v91, v30
	v_sub_f32_e32 v92, v92, v30
	v_sub_f32_e32 v93, v93, v30
	v_sub_f32_e32 v94, v94, v30
	v_sub_f32_e32 v95, v95, v30
	v_sub_f32_e32 v96, v96, v30
	v_sub_f32_e32 v97, v97, v30
	v_sub_f32_e32 v98, v98, v30
	v_sub_f32_e32 v99, v99, v30
	v_exp_f32_e32 v60, v60
	v_exp_f32_e32 v61, v61
	v_exp_f32_e32 v62, v62
	v_exp_f32_e32 v63, v63
	v_exp_f32_e32 v64, v64
	v_exp_f32_e32 v65, v65
	v_exp_f32_e32 v66, v66
	v_exp_f32_e32 v67, v67
	v_exp_f32_e32 v68, v68
	v_exp_f32_e32 v69, v69
	v_exp_f32_e32 v70, v70
	v_exp_f32_e32 v71, v71
	v_exp_f32_e32 v72, v72
	v_exp_f32_e32 v73, v73
	v_exp_f32_e32 v74, v74
	v_exp_f32_e32 v75, v75
	v_exp_f32_e32 v76, v76
	v_exp_f32_e32 v77, v77
	v_exp_f32_e32 v78, v78
	v_exp_f32_e32 v79, v79
	v_exp_f32_e32 v80, v80
	v_exp_f32_e32 v81, v81
	v_exp_f32_e32 v82, v82
	v_exp_f32_e32 v83, v83
	v_exp_f32_e32 v84, v84
	v_exp_f32_e32 v85, v85
	v_exp_f32_e32 v86, v86
	v_exp_f32_e32 v87, v87
	v_exp_f32_e32 v88, v88
	v_exp_f32_e32 v89, v89
	v_exp_f32_e32 v90, v90
	v_exp_f32_e32 v91, v91
	v_exp_f32_e32 v92, v92
	v_exp_f32_e32 v93, v93
	v_exp_f32_e32 v94, v94
	v_exp_f32_e32 v95, v95
	v_exp_f32_e32 v96, v96
	v_exp_f32_e32 v97, v97
	v_exp_f32_e32 v98, v98
	v_exp_f32_e32 v99, v99
	v_add_f32_e32 v31, v60, v61
	v_add_f32_e32 v31, v31, v62
	v_add_f32_e32 v31, v31, v63
	v_add_f32_e32 v31, v31, v64
	v_add_f32_e32 v31, v31, v65
	v_add_f32_e32 v31, v31, v66
	v_add_f32_e32 v31, v31, v67
	v_add_f32_e32 v31, v31, v68
	v_add_f32_e32 v31, v31, v69
	v_add_f32_e32 v31, v31, v70
	v_add_f32_e32 v31, v31, v71
	v_add_f32_e32 v31, v31, v72
	v_add_f32_e32 v31, v31, v73
	v_add_f32_e32 v31, v31, v74
	v_add_f32_e32 v31, v31, v75
	v_add_f32_e32 v31, v31, v76
	v_add_f32_e32 v31, v31, v77
	v_add_f32_e32 v31, v31, v78
	v_add_f32_e32 v31, v31, v79
	v_add_f32_e32 v31, v31, v80
	v_add_f32_e32 v31, v31, v81
	v_add_f32_e32 v31, v31, v82
	v_add_f32_e32 v31, v31, v83
	v_add_f32_e32 v31, v31, v84
	v_add_f32_e32 v31, v31, v85
	v_add_f32_e32 v31, v31, v86
	v_add_f32_e32 v31, v31, v87
	v_add_f32_e32 v31, v31, v88
	v_add_f32_e32 v31, v31, v89
	v_add_f32_e32 v31, v31, v90
	v_add_f32_e32 v31, v31, v91
	v_add_f32_e32 v31, v31, v92
	v_add_f32_e32 v31, v31, v93
	v_add_f32_e32 v31, v31, v94
	v_add_f32_e32 v31, v31, v95
	v_add_f32_e32 v31, v31, v96
	v_add_f32_e32 v31, v31, v97
	v_add_f32_e32 v31, v31, v98
	v_add_f32_e32 v31, v31, v99
	ds_bpermute_b32 v33, v28, v31
	s_waitcnt lgkmcnt(0)
	v_add_f32_e32 v31, v31, v33
	ds_bpermute_b32 v33, v29, v31
	s_waitcnt lgkmcnt(0)
	v_add_f32_e32 v31, v31, v33
	v_sub_f32_e32 v33, s84, v30
	v_exp_f32_e32 v33, v33
	s_nop 0
	v_add_f32_e32 v31, v31, v33
	v_rcp_f32_e32 v32, v31
	s_nop 0
	v_fma_f32 v33, -v31, v32, 2.0
	v_mul_f32_e32 v32, v32, v33
	v_mul_f32_e32 v60, v32, v60
	v_mul_f32_e32 v61, v32, v61
	v_cvt_pk_bf16_f32 v140, v60, v61
	v_mul_f32_e32 v62, v32, v62
	v_mul_f32_e32 v63, v32, v63
	v_cvt_pk_bf16_f32 v141, v62, v63
	v_mul_f32_e32 v64, v32, v64
	v_mul_f32_e32 v65, v32, v65
	v_cvt_pk_bf16_f32 v142, v64, v65
	v_mul_f32_e32 v66, v32, v66
	v_mul_f32_e32 v67, v32, v67
	v_cvt_pk_bf16_f32 v143, v66, v67
	v_mul_f32_e32 v68, v32, v68
	v_mul_f32_e32 v69, v32, v69
	v_cvt_pk_bf16_f32 v144, v68, v69
	v_mul_f32_e32 v70, v32, v70
	v_mul_f32_e32 v71, v32, v71
	v_cvt_pk_bf16_f32 v145, v70, v71
	v_mul_f32_e32 v72, v32, v72
	v_mul_f32_e32 v73, v32, v73
	v_cvt_pk_bf16_f32 v146, v72, v73
	v_mul_f32_e32 v74, v32, v74
	v_mul_f32_e32 v75, v32, v75
	v_cvt_pk_bf16_f32 v147, v74, v75
	v_mul_f32_e32 v76, v32, v76
	v_mul_f32_e32 v77, v32, v77
	v_cvt_pk_bf16_f32 v148, v76, v77
	v_mul_f32_e32 v78, v32, v78
	v_mul_f32_e32 v79, v32, v79
	v_cvt_pk_bf16_f32 v149, v78, v79
	v_mul_f32_e32 v80, v32, v80
	v_mul_f32_e32 v81, v32, v81
	v_cvt_pk_bf16_f32 v150, v80, v81
	v_mul_f32_e32 v82, v32, v82
	v_mul_f32_e32 v83, v32, v83
	v_cvt_pk_bf16_f32 v151, v82, v83
	v_mul_f32_e32 v84, v32, v84
	v_mul_f32_e32 v85, v32, v85
	v_cvt_pk_bf16_f32 v152, v84, v85
	v_mul_f32_e32 v86, v32, v86
	v_mul_f32_e32 v87, v32, v87
	v_cvt_pk_bf16_f32 v153, v86, v87
	v_mul_f32_e32 v88, v32, v88
	v_mul_f32_e32 v89, v32, v89
	v_cvt_pk_bf16_f32 v154, v88, v89
	v_mul_f32_e32 v90, v32, v90
	v_mul_f32_e32 v91, v32, v91
	v_cvt_pk_bf16_f32 v155, v90, v91
	v_mul_f32_e32 v92, v32, v92
	v_mul_f32_e32 v93, v32, v93
	v_cvt_pk_bf16_f32 v156, v92, v93
	v_mul_f32_e32 v94, v32, v94
	v_mul_f32_e32 v95, v32, v95
	v_cvt_pk_bf16_f32 v157, v94, v95
	v_mul_f32_e32 v96, v32, v96
	v_mul_f32_e32 v97, v32, v97
	v_cvt_pk_bf16_f32 v158, v96, v97
	v_mul_f32_e32 v98, v32, v98
	v_mul_f32_e32 v99, v32, v99
	v_cvt_pk_bf16_f32 v159, v98, v99
	ds_read_b64_tr_b16 v[196:197], v22 offset:0
	ds_read_b64_tr_b16 v[198:199], v22 offset:2048
	ds_read_b64_tr_b16 v[200:201], v23 offset:0
	ds_read_b64_tr_b16 v[202:203], v23 offset:2048
	ds_read_b64_tr_b16 v[204:205], v24 offset:0
	ds_read_b64_tr_b16 v[206:207], v24 offset:2048
	ds_read_b64_tr_b16 v[208:209], v25 offset:0
	ds_read_b64_tr_b16 v[210:211], v25 offset:2048
	ds_read_b64_tr_b16 v[220:221], v22 offset:4096
	ds_read_b64_tr_b16 v[222:223], v22 offset:6144
	ds_read_b64_tr_b16 v[224:225], v23 offset:4096
	ds_read_b64_tr_b16 v[226:227], v23 offset:6144
	ds_read_b64_tr_b16 v[228:229], v24 offset:4096
	ds_read_b64_tr_b16 v[230:231], v24 offset:6144
	ds_read_b64_tr_b16 v[232:233], v25 offset:4096
	ds_read_b64_tr_b16 v[234:235], v25 offset:6144
	s_waitcnt lgkmcnt(14)
; #define LAS __attribute__((address_space(3)))
; __device__ __forceinline__ unsigned pk_bf16(float lo, float hi) { const f32x2_t f = {lo, hi}; return __builtin_bit_cast(unsigned, __builtin_convertvector(f, bf16x2_t)); }
; __device__ __forceinline__ void phase_attn(const Params& p, int l, LAS unsigned char* ldsb) {
;     ...
; #pragma unroll
;             for (int kk = 0; kk < 5; ++kk) {
;                 const bf16x8 pa = *(LAS const bf16x8*)(Pw + fr * 168 + kk * 32 + fq * 8);
; #pragma unroll
;                 for (int dt = 0; dt < 4; ++dt) {
;                     const bf16x8 vb = *(LAS const bf16x8*)(Vt + (dt * 16 + fr) * 264 + kstart + kk * 32 + fq * 8);
;                     O[dt] = __builtin_amdgcn_mfma_f32_16x16x32_bf16(pa, vb, O[dt], 0, 0, 0);
;                 }
;             }
; #pragma unroll
;             for (int dt = 0; dt < 4; ++dt)
; #pragma unroll
;                 for (int j = 0; j < 4; ++j) ATT[(size_t)(tokc + q0 + 4 * fq + j) * 512 + hq * 64 + dt * 16 + fr] = (bf16_t)(pk_bf16(O[dt][j], 0.f) & 0xffffu);
;             asm volatile("s_waitcnt lgkmcnt(0)" ::: "memory");
;             __builtin_amdgcn_wave_barrier();
;         }
;         __syncthreads();
;     }
	v_mfma_f32_16x16x32_bf16 v[160:163], v[196:199], v[140:143], 0
	s_waitcnt lgkmcnt(12)
	v_mfma_f32_16x16x32_bf16 v[164:167], v[200:203], v[140:143], 0
	s_waitcnt lgkmcnt(10)
	v_mfma_f32_16x16x32_bf16 v[168:171], v[204:207], v[140:143], 0
	s_waitcnt lgkmcnt(8)
	v_mfma_f32_16x16x32_bf16 v[172:175], v[208:211], v[140:143], 0
	ds_read_b64_tr_b16 v[196:197], v22 offset:8192
	ds_read_b64_tr_b16 v[198:199], v22 offset:10240
	ds_read_b64_tr_b16 v[200:201], v23 offset:8192
	ds_read_b64_tr_b16 v[202:203], v23 offset:10240
	ds_read_b64_tr_b16 v[204:205], v24 offset:8192
	ds_read_b64_tr_b16 v[206:207], v24 offset:10240
	ds_read_b64_tr_b16 v[208:209], v25 offset:8192
	ds_read_b64_tr_b16 v[210:211], v25 offset:10240
	s_waitcnt lgkmcnt(14)
	v_mfma_f32_16x16x32_bf16 v[160:163], v[220:223], v[144:147], v[160:163]
	s_waitcnt lgkmcnt(12)
	v_mfma_f32_16x16x32_bf16 v[164:167], v[224:227], v[144:147], v[164:167]
	s_waitcnt lgkmcnt(10)
	v_mfma_f32_16x16x32_bf16 v[168:171], v[228:231], v[144:147], v[168:171]
	s_waitcnt lgkmcnt(8)
	v_mfma_f32_16x16x32_bf16 v[172:175], v[232:235], v[144:147], v[172:175]
	ds_read_b64_tr_b16 v[220:221], v22 offset:12288
	ds_read_b64_tr_b16 v[222:223], v22 offset:14336
	ds_read_b64_tr_b16 v[224:225], v23 offset:12288
	ds_read_b64_tr_b16 v[226:227], v23 offset:14336
	ds_read_b64_tr_b16 v[228:229], v24 offset:12288
	ds_read_b64_tr_b16 v[230:231], v24 offset:14336
	ds_read_b64_tr_b16 v[232:233], v25 offset:12288
	ds_read_b64_tr_b16 v[234:235], v25 offset:14336
	s_waitcnt lgkmcnt(14)
	v_mfma_f32_16x16x32_bf16 v[160:163], v[196:199], v[148:151], v[160:163]
	s_waitcnt lgkmcnt(12)
	v_mfma_f32_16x16x32_bf16 v[164:167], v[200:203], v[148:151], v[164:167]
	s_waitcnt lgkmcnt(10)
	v_mfma_f32_16x16x32_bf16 v[168:171], v[204:207], v[148:151], v[168:171]
	s_waitcnt lgkmcnt(8)
	v_mfma_f32_16x16x32_bf16 v[172:175], v[208:211], v[148:151], v[172:175]
	ds_read_b64_tr_b16 v[196:197], v22 offset:16384
	ds_read_b64_tr_b16 v[198:199], v22 offset:18432
	ds_read_b64_tr_b16 v[200:201], v23 offset:16384
	ds_read_b64_tr_b16 v[202:203], v23 offset:18432
	ds_read_b64_tr_b16 v[204:205], v24 offset:16384
	ds_read_b64_tr_b16 v[206:207], v24 offset:18432
	ds_read_b64_tr_b16 v[208:209], v25 offset:16384
	ds_read_b64_tr_b16 v[210:211], v25 offset:18432
	s_waitcnt lgkmcnt(14)
	v_mfma_f32_16x16x32_bf16 v[160:163], v[220:223], v[152:155], v[160:163]
	s_waitcnt lgkmcnt(12)
	v_mfma_f32_16x16x32_bf16 v[164:167], v[224:227], v[152:155], v[164:167]
	s_waitcnt lgkmcnt(10)
	v_mfma_f32_16x16x32_bf16 v[168:171], v[228:231], v[152:155], v[168:171]
	s_waitcnt lgkmcnt(8)
	v_mfma_f32_16x16x32_bf16 v[172:175], v[232:235], v[152:155], v[172:175]
	s_waitcnt lgkmcnt(6)
	v_mfma_f32_16x16x32_bf16 v[160:163], v[196:199], v[156:159], v[160:163]
	s_waitcnt lgkmcnt(4)
	v_mfma_f32_16x16x32_bf16 v[164:167], v[200:203], v[156:159], v[164:167]
	s_waitcnt lgkmcnt(2)
	v_mfma_f32_16x16x32_bf16 v[168:171], v[204:207], v[156:159], v[168:171]
	s_waitcnt lgkmcnt(0)
	v_mfma_f32_16x16x32_bf16 v[172:175], v[208:211], v[156:159], v[172:175]
	s_nop 1
	v_cvt_pk_bf16_f32 v176, v160, v161
	v_cvt_pk_bf16_f32 v177, v162, v163
	global_store_dwordx2 v27, v[176:177], s[42:43] offset:0
	v_cvt_pk_bf16_f32 v176, v164, v165
	v_cvt_pk_bf16_f32 v177, v166, v167
	global_store_dwordx2 v27, v[176:177], s[42:43] offset:32
	v_cvt_pk_bf16_f32 v176, v168, v169
	v_cvt_pk_bf16_f32 v177, v170, v171
	global_store_dwordx2 v27, v[176:177], s[42:43] offset:64
	v_cvt_pk_bf16_f32 v176, v172, v173
	v_cvt_pk_bf16_f32 v177, v174, v175
	global_store_dwordx2 v27, v[176:177], s[42:43] offset:96
	s_add_u32 s49, s49, 1
	s_cmp_lt_u32 s49, 4
	s_cbranch_scc1 .Lat_rt
	s_waitcnt lgkmcnt(0)
	s_barrier
	s_add_u32 s2, s2, s62
	s_cmp_lt_u32 s2, 512
	s_cbranch_scc1 .Lat_item
.Lat_end:
	v_readlane_b32 s52, v243, 41
	v_readlane_b32 s53, v243, 42
	v_readlane_b32 s80, v252, 4
	v_readlane_b32 s81, v252, 5
	v_readlane_b32 s82, v252, 6
	v_readlane_b32 s83, v252, 7
	v_readlane_b32 s84, v252, 8
	v_readlane_b32 s85, v252, 9
	v_readlane_b32 s86, v252, 10
	v_readlane_b32 s87, v252, 11
	v_readlane_b32 s88, v252, 12
	v_readlane_b32 s89, v252, 13
	v_readlane_b32 s90, v252, 14
	v_readlane_b32 s91, v252, 15
	v_readlane_b32 s92, v252, 16
	v_readlane_b32 s93, v252, 17
	v_readlane_b32 s94, v252, 18
	v_readlane_b32 s95, v252, 19
	s_waitcnt vmcnt(0)
